# phase 9 Q epilogue: 8 per-row rstd loads issued together behind the first (one wait covers all), on top of KV epilogue hoist and counted-wait version
# baseline (speedup 1.0000x reference)
; __device__ __forceinline__ f32x4 rope2(const f32x4 x, float c0, float s0, float c1, float s1) { return (f32x4){x[0] * c0 - x[1] * s0, x[1] * c0 + x[0] * s0, x[2] * c1 - x[3] * s1, x[3] * c1 + x[2] * s1}; }
;     __device__ __forceinline__ void operator()(const f32x4 (&acc)[2][2][4][2], const pg8::Unit& u, int wr, int wc, int fr, int fq) const {
;         const int row0 = u.pm * 256 + wr * 64 + fr, cw = wc * 32 + 8 * fq;
; #pragma unroll
;         for (int ai = 0; ai < 2; ++ai)
; #pragma unroll
;             for (int m = 0; m < 4; ++m) {
;                 const int row = row0 + ai * 128 + m * 16;
;                 const float rs = 1.0f / sqrtf(SS[(size_t)row * 2] * (1.0f / 512.0f) + 1e-6f);
; #pragma unroll
;                 for (int bj = 0; bj < 2; ++bj) {
;                     const int col8 = u.pn * 256 + bj * 128 + cw, d = col8 % 192;
;                     f32x4 v0 = acc[ai][bj][m][0] * rs, v1 = acc[ai][bj][m][1] * rs;
;                     if (d >= 128) {
;                         const int p0 = (d - 128) >> 1;
;                         const f32x4 c4 = *(const f32x4*)(cosR + (size_t)row * 32 + p0), s4 = *(const f32x4*)(sinR + (size_t)row * 32 + p0);
;                         v0 = rope2(v0, c4[0], s4[0], c4[1], s4[1]); v1 = rope2(v1, c4[2], s4[2], c4[3], s4[3]);
;                     }
.LBB0_998:
	v_lshl_add_u32 v148, s27, 8, v157
	v_ashrrev_i32_e32 v149, 31, v148
	v_lshl_add_u64 v[146:147], v[148:149], 3, s[16:17]
	global_load_dword v136, v[146:147], off
	global_load_dword v246, v[146:147], off offset:128
	global_load_dword v247, v[146:147], off offset:256
	global_load_dword v248, v[146:147], off offset:384
	global_load_dword v249, v[146:147], off offset:1024
	global_load_dword v250, v[146:147], off offset:1152
	global_load_dword v251, v[146:147], off offset:1280
	global_load_dword v252, v[146:147], off offset:1408
	v_lshl_or_b32 v146, s26, 8, v159
	v_mul_hi_i32 v147, v146, s81
	v_lshlrev_b64 v[150:151], 5, v[148:149]
	v_lshrrev_b32_e32 v149, 31, v147
	v_lshrrev_b32_e32 v147, 5, v147
	v_add_u32_e32 v147, v147, v149
	v_mul_lo_u32 v147, v147, s64
	v_sub_u32_e32 v147, v146, v147
	v_cmp_lt_i32_e64 s[8:9], s85, v147
	v_add_u32_e32 v147, 0xffffff80, v147
	v_lshlrev_b64 v[178:179], 2, v[150:151]
	v_lshl_add_u64 v[150:151], s[42:43], 0, v[178:179]
	s_waitcnt vmcnt(0)
	v_fmamk_f32 v136, v136, 0x3b000000, v176
	v_mul_f32_e32 v149, 0x4f800000, v136
	v_cmp_gt_f32_e32 vcc, s84, v136
	s_nop 1
	v_cndmask_b32_e32 v136, v136, v149, vcc
	v_sqrt_f32_e32 v149, v136
	s_nop 0
	v_add_u32_e32 v152, -1, v149
	v_add_u32_e32 v153, 1, v149
	v_fma_f32 v154, -v152, v149, v136
	v_fma_f32 v155, -v153, v149, v136
	v_cmp_ge_f32_e64 s[10:11], 0, v154
	s_nop 1
	v_cndmask_b32_e64 v149, v149, v152, s[10:11]
	v_cmp_lt_f32_e64 s[10:11], 0, v155
	s_nop 1
	v_cndmask_b32_e64 v149, v149, v153, s[10:11]
	v_mul_f32_e32 v152, 0x37800000, v149
	v_cndmask_b32_e32 v149, v149, v152, vcc
	v_cmp_class_f32_e32 vcc, v136, v177
	s_nop 1
	v_cndmask_b32_e32 v149, v149, v136, vcc
	v_div_scale_f32 v152, s[10:11], v149, v149, 1.0
	v_rcp_f32_e32 v153, v152
	v_lshrrev_b32_e32 v136, 1, v147
	v_div_scale_f32 v147, vcc, 1.0, v149, 1.0
	v_fma_f32 v154, -v152, v153, 1.0
	v_fmac_f32_e32 v153, v154, v153
	v_mul_f32_e32 v154, v147, v153
	v_fma_f32 v155, -v152, v154, v147
	v_fmac_f32_e32 v154, v155, v153
	v_fma_f32 v147, -v152, v154, v147
	v_div_fmas_f32 v147, v147, v153, v154
	v_div_fixup_f32 v152, v147, v149, 1.0
	v_pk_mul_f32 v[126:127], v[126:127], v[152:153] op_sel_hi:[1,0]
	v_pk_mul_f32 v[124:125], v[124:125], v[152:153] op_sel_hi:[1,0]
	v_pk_mul_f32 v[154:155], v[122:123], v[152:153] op_sel_hi:[1,0]
	v_pk_mul_f32 v[122:123], v[120:121], v[152:153] op_sel_hi:[1,0]
	v_lshl_add_u64 v[120:121], s[44:45], 0, v[178:179]
	s_and_saveexec_b64 s[10:11], s[8:9]
	s_cbranch_execz .LBB0_1000
	v_lshlrev_b64 v[178:179], 2, v[136:137]
	v_lshl_add_u64 v[180:181], v[150:151], 0, v[178:179]
	v_lshl_add_u64 v[182:183], v[120:121], 0, v[178:179]
	global_load_dwordx4 v[178:181], v[180:181], off
	s_nop 0
	global_load_dwordx4 v[182:185], v[182:183], off
	s_waitcnt vmcnt(0)
	v_pk_mul_f32 v[186:187], v[124:125], v[178:179]
	v_pk_mul_f32 v[188:189], v[124:125], v[182:183] op_sel:[1,0] op_sel_hi:[0,0]
	v_pk_mul_f32 v[196:197], v[122:123], v[184:185] op_sel:[1,0] op_sel_hi:[0,0]
	v_mov_b32_e32 v182, v179
	v_mul_f32_e32 v190, v127, v183
	v_mul_f32_e32 v192, v127, v179
	v_pk_mul_f32 v[194:195], v[122:123], v[180:181]
	v_mov_b32_e32 v184, v181
	v_mul_f32_e32 v198, v155, v185
	v_mul_f32_e32 v200, v155, v181
	v_pk_fma_f32 v[124:125], v[124:125], v[178:179], v[188:189] op_sel_hi:[1,0,1]
	v_mov_b32_e32 v178, v183
	v_pk_fma_f32 v[122:123], v[122:123], v[180:181], v[196:197] op_sel_hi:[1,0,1]
	v_mov_b32_e32 v180, v185
	v_pk_fma_f32 v[190:191], v[126:127], v[182:183], v[190:191] op_sel_hi:[1,1,0] neg_lo:[0,0,1] neg_hi:[0,0,1]
	v_pk_fma_f32 v[182:183], v[154:155], v[184:185], v[198:199] op_sel_hi:[1,1,0] neg_lo:[0,0,1] neg_hi:[0,0,1]
	v_pk_fma_f32 v[178:179], v[126:127], v[178:179], v[192:193] op_sel_hi:[1,1,0]
	v_pk_fma_f32 v[180:181], v[154:155], v[180:181], v[200:201] op_sel_hi:[1,1,0]
	v_sub_f32_e32 v124, v186, v188
	v_sub_f32_e32 v122, v194, v196
	v_mov_b32_e32 v126, v190
	v_mov_b32_e32 v154, v182
	v_mov_b32_e32 v127, v178
	v_mov_b32_e32 v155, v180

; __device__ __forceinline__ u32x4 pack8(const f32x4 a, const f32x4 b) { u32x4 w; w.x = cvt_pk_bf16(a[0], a[1]); w.y = cvt_pk_bf16(a[2], a[3]); w.z = cvt_pk_bf16(b[0], b[1]); w.w = cvt_pk_bf16(b[2], b[3]); return w; }
; __device__ __forceinline__ f32x4 rope2(const f32x4 x, float c0, float s0, float c1, float s1) { return (f32x4){x[0] * c0 - x[1] * s0, x[1] * c0 + x[0] * s0, x[2] * c1 - x[3] * s1, x[3] * c1 + x[2] * s1}; }
;     __device__ __forceinline__ void operator()(const f32x4 (&acc)[2][2][4][2], const pg8::Unit& u, int wr, int wc, int fr, int fq) const {
;     ...
;                 const int row = row0 + ai * 128 + m * 16;
;                 const float rs = 1.0f / sqrtf(SS[(size_t)row * 2] * (1.0f / 512.0f) + 1e-6f);
; #pragma unroll
;                 for (int bj = 0; bj < 2; ++bj) {
;                     const int col8 = u.pn * 256 + bj * 128 + cw, d = col8 % 192;
;                     f32x4 v0 = acc[ai][bj][m][0] * rs, v1 = acc[ai][bj][m][1] * rs;
;                     if (d >= 128) {
;                         const int p0 = (d - 128) >> 1;
;                         const f32x4 c4 = *(const f32x4*)(cosR + (size_t)row * 32 + p0), s4 = *(const f32x4*)(sinR + (size_t)row * 32 + p0);
;                         v0 = rope2(v0, c4[0], s4[0], c4[1], s4[1]); v1 = rope2(v1, c4[2], s4[2], c4[3], s4[3]);
;                     }
;                     *(u32x4*)(QM + (size_t)row * 3072 + col8) = pack8(v0, v1);
.LBB0_1002:
	s_or_b64 exec, exec, s[12:13]
	v_cvt_pk_bf16_f32 v116, v116, v117
	v_cvt_pk_bf16_f32 v117, v118, v119
	v_cvt_pk_bf16_f32 v118, v114, v115
	v_or_b32_e32 v114, 16, v148
	v_cvt_pk_bf16_f32 v119, v124, v125
	global_store_dwordx4 v[122:123], v[116:119], off offset:256
	v_ashrrev_i32_e32 v115, 31, v114
	s_nop 0
	v_lshl_add_u64 v[116:117], v[114:115], 3, s[16:17]
	v_mov_b32_e32 v113, v246
	v_fmamk_f32 v113, v113, 0x3b000000, v176
	v_mul_f32_e32 v116, 0x4f800000, v113
	v_cmp_gt_f32_e32 vcc, s84, v113
	s_nop 1
	v_cndmask_b32_e32 v113, v113, v116, vcc
	v_sqrt_f32_e32 v118, v113
	v_lshlrev_b64 v[116:117], 5, v[114:115]
	v_lshlrev_b64 v[122:123], 2, v[116:117]
	v_add_u32_e32 v115, -1, v118
	v_add_u32_e32 v116, 1, v118
	v_fma_f32 v117, -v115, v118, v113
	v_fma_f32 v119, -v116, v118, v113
	v_cmp_ge_f32_e64 s[12:13], 0, v117
	s_nop 1
	v_cndmask_b32_e64 v115, v118, v115, s[12:13]
	v_cmp_lt_f32_e64 s[12:13], 0, v119
	s_nop 1
	v_cndmask_b32_e64 v115, v115, v116, s[12:13]
	v_mul_f32_e32 v116, 0x37800000, v115
	v_cndmask_b32_e32 v115, v115, v116, vcc
	v_cmp_class_f32_e32 vcc, v113, v177
	v_lshl_add_u64 v[116:117], s[42:43], 0, v[122:123]
	s_nop 0
	v_cndmask_b32_e32 v113, v115, v113, vcc
	v_div_scale_f32 v115, s[12:13], v113, v113, 1.0
	v_rcp_f32_e32 v118, v115
	v_div_scale_f32 v119, vcc, 1.0, v113, 1.0
	v_fma_f32 v120, -v115, v118, 1.0
	v_fmac_f32_e32 v118, v120, v118
	v_mul_f32_e32 v120, v119, v118
	v_fma_f32 v121, -v115, v120, v119
	v_fmac_f32_e32 v120, v121, v118
	v_fma_f32 v115, -v115, v120, v119
	v_div_fmas_f32 v115, v115, v118, v120
	v_div_fixup_f32 v118, v115, v113, 1.0
	v_pk_mul_f32 v[110:111], v[110:111], v[118:119] op_sel_hi:[1,0]
	v_pk_mul_f32 v[108:109], v[108:109], v[118:119] op_sel_hi:[1,0]
	v_pk_mul_f32 v[120:121], v[106:107], v[118:119] op_sel_hi:[1,0]
	v_pk_mul_f32 v[106:107], v[104:105], v[118:119] op_sel_hi:[1,0]
	v_lshl_add_u64 v[104:105], s[44:45], 0, v[122:123]
	s_and_saveexec_b64 s[12:13], s[8:9]
	s_cbranch_execz .LBB0_1004
	v_lshlrev_b64 v[122:123], 2, v[136:137]
	v_lshl_add_u64 v[124:125], v[116:117], 0, v[122:123]
	v_lshl_add_u64 v[126:127], v[104:105], 0, v[122:123]
	global_load_dwordx4 v[122:125], v[124:125], off
	s_nop 0
	global_load_dwordx4 v[150:153], v[126:127], off
	s_waitcnt vmcnt(0)
	v_pk_mul_f32 v[126:127], v[108:109], v[122:123]
	v_pk_mul_f32 v[154:155], v[108:109], v[150:151] op_sel:[1,0] op_sel_hi:[0,0]
	v_pk_mul_f32 v[184:185], v[106:107], v[152:153] op_sel:[1,0] op_sel_hi:[0,0]
	v_mov_b32_e32 v150, v123
	v_mul_f32_e32 v178, v111, v151
	v_mul_f32_e32 v180, v111, v123
	v_pk_mul_f32 v[182:183], v[106:107], v[124:125]
	v_mov_b32_e32 v152, v125
	v_mul_f32_e32 v186, v121, v153
	v_mul_f32_e32 v188, v121, v125
	v_pk_fma_f32 v[108:109], v[108:109], v[122:123], v[154:155] op_sel_hi:[1,0,1]
	v_mov_b32_e32 v122, v151
	v_pk_fma_f32 v[106:107], v[106:107], v[124:125], v[184:185] op_sel_hi:[1,0,1]
	v_mov_b32_e32 v124, v153
	v_pk_fma_f32 v[178:179], v[110:111], v[150:151], v[178:179] op_sel_hi:[1,1,0] neg_lo:[0,0,1] neg_hi:[0,0,1]
	v_pk_fma_f32 v[150:151], v[120:121], v[152:153], v[186:187] op_sel_hi:[1,1,0] neg_lo:[0,0,1] neg_hi:[0,0,1]
	v_pk_fma_f32 v[122:123], v[110:111], v[122:123], v[180:181] op_sel_hi:[1,1,0]
	v_pk_fma_f32 v[124:125], v[120:121], v[124:125], v[188:189] op_sel_hi:[1,1,0]
	v_sub_f32_e32 v108, v126, v154
	v_sub_f32_e32 v106, v182, v184
	v_mov_b32_e32 v110, v178
	v_mov_b32_e32 v120, v150
	v_mov_b32_e32 v111, v122
	v_mov_b32_e32 v121, v124

; __device__ __forceinline__ u32x4 pack8(const f32x4 a, const f32x4 b) { u32x4 w; w.x = cvt_pk_bf16(a[0], a[1]); w.y = cvt_pk_bf16(a[2], a[3]); w.z = cvt_pk_bf16(b[0], b[1]); w.w = cvt_pk_bf16(b[2], b[3]); return w; }
; __device__ __forceinline__ f32x4 rope2(const f32x4 x, float c0, float s0, float c1, float s1) { return (f32x4){x[0] * c0 - x[1] * s0, x[1] * c0 + x[0] * s0, x[2] * c1 - x[3] * s1, x[3] * c1 + x[2] * s1}; }
;     __device__ __forceinline__ void operator()(const f32x4 (&acc)[2][2][4][2], const pg8::Unit& u, int wr, int wc, int fr, int fq) const {
;     ...
;                 const int row = row0 + ai * 128 + m * 16;
;                 const float rs = 1.0f / sqrtf(SS[(size_t)row * 2] * (1.0f / 512.0f) + 1e-6f);
; #pragma unroll
;                 for (int bj = 0; bj < 2; ++bj) {
;                     const int col8 = u.pn * 256 + bj * 128 + cw, d = col8 % 192;
;                     f32x4 v0 = acc[ai][bj][m][0] * rs, v1 = acc[ai][bj][m][1] * rs;
;                     if (d >= 128) {
;                         const int p0 = (d - 128) >> 1;
;                         const f32x4 c4 = *(const f32x4*)(cosR + (size_t)row * 32 + p0), s4 = *(const f32x4*)(sinR + (size_t)row * 32 + p0);
;                         v0 = rope2(v0, c4[0], s4[0], c4[1], s4[1]); v1 = rope2(v1, c4[2], s4[2], c4[3], s4[3]);
;                     }
;                     *(u32x4*)(QM + (size_t)row * 3072 + col8) = pack8(v0, v1);
.LBB0_1006:
	s_or_b64 exec, exec, s[12:13]
	v_cvt_pk_bf16_f32 v100, v100, v101
	v_cvt_pk_bf16_f32 v101, v102, v103
	v_cvt_pk_bf16_f32 v102, v96, v97
	v_or_b32_e32 v96, 32, v148
	v_cvt_pk_bf16_f32 v103, v98, v99
	global_store_dwordx4 v[106:107], v[100:103], off offset:256
	v_ashrrev_i32_e32 v97, 31, v96
	v_lshl_add_u64 v[98:99], v[96:97], 3, s[16:17]
	v_mov_b32_e32 v98, v247
	v_fmamk_f32 v98, v98, 0x3b000000, v176
	v_mul_f32_e32 v99, 0x4f800000, v98
	v_cmp_gt_f32_e32 vcc, s84, v98
	s_nop 1
	v_cndmask_b32_e32 v100, v98, v99, vcc
	v_sqrt_f32_e32 v101, v100
	v_lshlrev_b64 v[98:99], 5, v[96:97]
	v_lshlrev_b64 v[104:105], 2, v[98:99]
	v_add_u32_e32 v97, -1, v101
	v_add_u32_e32 v98, 1, v101
	v_fma_f32 v99, -v97, v101, v100
	v_fma_f32 v102, -v98, v101, v100
	v_cmp_ge_f32_e64 s[12:13], 0, v99
	s_nop 1
	v_cndmask_b32_e64 v97, v101, v97, s[12:13]
	v_cmp_lt_f32_e64 s[12:13], 0, v102
	s_nop 1
	v_cndmask_b32_e64 v97, v97, v98, s[12:13]
	v_mul_f32_e32 v98, 0x37800000, v97
	v_cndmask_b32_e32 v97, v97, v98, vcc
	v_cmp_class_f32_e32 vcc, v100, v177
	v_lshl_add_u64 v[98:99], s[42:43], 0, v[104:105]
	s_nop 0
	v_cndmask_b32_e32 v97, v97, v100, vcc
	v_div_scale_f32 v100, s[12:13], v97, v97, 1.0
	v_rcp_f32_e32 v101, v100
	v_div_scale_f32 v102, vcc, 1.0, v97, 1.0
	v_fma_f32 v103, -v100, v101, 1.0
	v_fmac_f32_e32 v101, v103, v101
	v_mul_f32_e32 v103, v102, v101
	v_fma_f32 v106, -v100, v103, v102
	v_fmac_f32_e32 v103, v106, v101
	v_fma_f32 v100, -v100, v103, v102
	v_div_fmas_f32 v100, v100, v101, v103
	v_div_fixup_f32 v100, v100, v97, 1.0
	v_pk_mul_f32 v[94:95], v[94:95], v[100:101] op_sel_hi:[1,0]
	v_pk_mul_f32 v[92:93], v[92:93], v[100:101] op_sel_hi:[1,0]
	v_pk_mul_f32 v[102:103], v[90:91], v[100:101] op_sel_hi:[1,0]
	v_pk_mul_f32 v[90:91], v[88:89], v[100:101] op_sel_hi:[1,0]
	v_lshl_add_u64 v[88:89], s[44:45], 0, v[104:105]
	s_and_saveexec_b64 s[12:13], s[8:9]
	s_cbranch_execz .LBB0_1008
	v_lshlrev_b64 v[104:105], 2, v[136:137]
	v_lshl_add_u64 v[106:107], v[98:99], 0, v[104:105]
	v_lshl_add_u64 v[108:109], v[88:89], 0, v[104:105]
	global_load_dwordx4 v[104:107], v[106:107], off
	s_nop 0
	global_load_dwordx4 v[108:111], v[108:109], off
	s_waitcnt vmcnt(0)
	v_pk_mul_f32 v[114:115], v[92:93], v[104:105]
	v_pk_mul_f32 v[116:117], v[92:93], v[108:109] op_sel:[1,0] op_sel_hi:[0,0]
	v_pk_mul_f32 v[124:125], v[90:91], v[110:111] op_sel:[1,0] op_sel_hi:[0,0]
	v_mov_b32_e32 v108, v105
	v_mul_f32_e32 v118, v95, v109
	v_mul_f32_e32 v120, v95, v105
	v_pk_mul_f32 v[122:123], v[90:91], v[106:107]
	v_mov_b32_e32 v110, v107
	v_mul_f32_e32 v126, v103, v111
	v_mul_f32_e32 v150, v103, v107
	v_pk_fma_f32 v[92:93], v[92:93], v[104:105], v[116:117] op_sel_hi:[1,0,1]
	v_mov_b32_e32 v104, v109
	v_pk_fma_f32 v[90:91], v[90:91], v[106:107], v[124:125] op_sel_hi:[1,0,1]
	v_mov_b32_e32 v106, v111
	v_pk_fma_f32 v[118:119], v[94:95], v[108:109], v[118:119] op_sel_hi:[1,1,0] neg_lo:[0,0,1] neg_hi:[0,0,1]
	v_pk_fma_f32 v[108:109], v[102:103], v[110:111], v[126:127] op_sel_hi:[1,1,0] neg_lo:[0,0,1] neg_hi:[0,0,1]
	v_pk_fma_f32 v[104:105], v[94:95], v[104:105], v[120:121] op_sel_hi:[1,1,0]
	v_pk_fma_f32 v[106:107], v[102:103], v[106:107], v[150:151] op_sel_hi:[1,1,0]
	v_sub_f32_e32 v92, v114, v116
	v_sub_f32_e32 v90, v122, v124
	v_mov_b32_e32 v94, v118
	v_mov_b32_e32 v102, v108
	v_mov_b32_e32 v95, v104
	v_mov_b32_e32 v103, v106

; __device__ __forceinline__ u32x4 pack8(const f32x4 a, const f32x4 b) { u32x4 w; w.x = cvt_pk_bf16(a[0], a[1]); w.y = cvt_pk_bf16(a[2], a[3]); w.z = cvt_pk_bf16(b[0], b[1]); w.w = cvt_pk_bf16(b[2], b[3]); return w; }
; __device__ __forceinline__ f32x4 rope2(const f32x4 x, float c0, float s0, float c1, float s1) { return (f32x4){x[0] * c0 - x[1] * s0, x[1] * c0 + x[0] * s0, x[2] * c1 - x[3] * s1, x[3] * c1 + x[2] * s1}; }
;     __device__ __forceinline__ void operator()(const f32x4 (&acc)[2][2][4][2], const pg8::Unit& u, int wr, int wc, int fr, int fq) const {
;     ...
;                 const int row = row0 + ai * 128 + m * 16;
;                 const float rs = 1.0f / sqrtf(SS[(size_t)row * 2] * (1.0f / 512.0f) + 1e-6f);
; #pragma unroll
;                 for (int bj = 0; bj < 2; ++bj) {
;                     const int col8 = u.pn * 256 + bj * 128 + cw, d = col8 % 192;
;                     f32x4 v0 = acc[ai][bj][m][0] * rs, v1 = acc[ai][bj][m][1] * rs;
;                     if (d >= 128) {
;                         const int p0 = (d - 128) >> 1;
;                         const f32x4 c4 = *(const f32x4*)(cosR + (size_t)row * 32 + p0), s4 = *(const f32x4*)(sinR + (size_t)row * 32 + p0);
;                         v0 = rope2(v0, c4[0], s4[0], c4[1], s4[1]); v1 = rope2(v1, c4[2], s4[2], c4[3], s4[3]);
;                     }
;                     *(u32x4*)(QM + (size_t)row * 3072 + col8) = pack8(v0, v1);
.LBB0_1010:
	s_or_b64 exec, exec, s[12:13]
	v_cvt_pk_bf16_f32 v84, v84, v85
	v_cvt_pk_bf16_f32 v85, v86, v87
	v_cvt_pk_bf16_f32 v86, v80, v81
	v_or_b32_e32 v80, 48, v148
	v_cvt_pk_bf16_f32 v87, v82, v83
	global_store_dwordx4 v[90:91], v[84:87], off offset:256
	v_ashrrev_i32_e32 v81, 31, v80
	v_lshl_add_u64 v[82:83], v[80:81], 3, s[16:17]
	v_mov_b32_e32 v82, v248
	v_fmamk_f32 v82, v82, 0x3b000000, v176
	v_mul_f32_e32 v83, 0x4f800000, v82
	v_cmp_gt_f32_e32 vcc, s84, v82
	s_nop 1
	v_cndmask_b32_e32 v84, v82, v83, vcc
	v_sqrt_f32_e32 v85, v84
	v_lshlrev_b64 v[82:83], 5, v[80:81]
	v_lshlrev_b64 v[88:89], 2, v[82:83]
	v_add_u32_e32 v81, -1, v85
	v_add_u32_e32 v82, 1, v85
	v_fma_f32 v83, -v81, v85, v84
	v_fma_f32 v86, -v82, v85, v84
	v_cmp_ge_f32_e64 s[12:13], 0, v83
	s_nop 1
	v_cndmask_b32_e64 v81, v85, v81, s[12:13]
	v_cmp_lt_f32_e64 s[12:13], 0, v86
	s_nop 1
	v_cndmask_b32_e64 v81, v81, v82, s[12:13]
	v_mul_f32_e32 v82, 0x37800000, v81
	v_cndmask_b32_e32 v81, v81, v82, vcc
	v_cmp_class_f32_e32 vcc, v84, v177
	v_lshl_add_u64 v[82:83], s[42:43], 0, v[88:89]
	s_nop 0
	v_cndmask_b32_e32 v81, v81, v84, vcc
	v_div_scale_f32 v84, s[12:13], v81, v81, 1.0
	v_rcp_f32_e32 v85, v84
	v_div_scale_f32 v86, vcc, 1.0, v81, 1.0
	v_fma_f32 v87, -v84, v85, 1.0
	v_fmac_f32_e32 v85, v87, v85
	v_mul_f32_e32 v87, v86, v85
	v_fma_f32 v90, -v84, v87, v86
	v_fmac_f32_e32 v87, v90, v85
	v_fma_f32 v84, -v84, v87, v86
	v_div_fmas_f32 v84, v84, v85, v87
	v_div_fixup_f32 v84, v84, v81, 1.0
	v_pk_mul_f32 v[78:79], v[78:79], v[84:85] op_sel_hi:[1,0]
	v_pk_mul_f32 v[76:77], v[76:77], v[84:85] op_sel_hi:[1,0]
	v_pk_mul_f32 v[86:87], v[74:75], v[84:85] op_sel_hi:[1,0]
	v_pk_mul_f32 v[74:75], v[72:73], v[84:85] op_sel_hi:[1,0]
	v_lshl_add_u64 v[72:73], s[44:45], 0, v[88:89]
	s_and_saveexec_b64 s[12:13], s[8:9]
	s_cbranch_execz .LBB0_1012
	v_lshlrev_b64 v[88:89], 2, v[136:137]
	v_lshl_add_u64 v[90:91], v[82:83], 0, v[88:89]
	v_lshl_add_u64 v[92:93], v[72:73], 0, v[88:89]
	global_load_dwordx4 v[88:91], v[90:91], off
	s_nop 0
	global_load_dwordx4 v[92:95], v[92:93], off
	s_waitcnt vmcnt(0)
	v_pk_mul_f32 v[96:97], v[76:77], v[88:89]
	v_pk_mul_f32 v[98:99], v[76:77], v[92:93] op_sel:[1,0] op_sel_hi:[0,0]
	v_pk_mul_f32 v[106:107], v[74:75], v[94:95] op_sel:[1,0] op_sel_hi:[0,0]
	v_mov_b32_e32 v92, v89
	v_mul_f32_e32 v100, v79, v93
	v_mul_f32_e32 v102, v79, v89
	v_pk_mul_f32 v[104:105], v[74:75], v[90:91]
	v_mov_b32_e32 v94, v91
	v_mul_f32_e32 v108, v87, v95
	v_mul_f32_e32 v110, v87, v91
	v_pk_fma_f32 v[76:77], v[76:77], v[88:89], v[98:99] op_sel_hi:[1,0,1]
	v_mov_b32_e32 v88, v93
	v_pk_fma_f32 v[74:75], v[74:75], v[90:91], v[106:107] op_sel_hi:[1,0,1]
	v_mov_b32_e32 v90, v95
	v_pk_fma_f32 v[100:101], v[78:79], v[92:93], v[100:101] op_sel_hi:[1,1,0] neg_lo:[0,0,1] neg_hi:[0,0,1]
	v_pk_fma_f32 v[92:93], v[86:87], v[94:95], v[108:109] op_sel_hi:[1,1,0] neg_lo:[0,0,1] neg_hi:[0,0,1]
	v_pk_fma_f32 v[88:89], v[78:79], v[88:89], v[102:103] op_sel_hi:[1,1,0]
	v_pk_fma_f32 v[90:91], v[86:87], v[90:91], v[110:111] op_sel_hi:[1,1,0]
	v_sub_f32_e32 v76, v96, v98
	v_sub_f32_e32 v74, v104, v106
	v_mov_b32_e32 v78, v100
	v_mov_b32_e32 v86, v92
	v_mov_b32_e32 v79, v88
	v_mov_b32_e32 v87, v90

; __device__ __forceinline__ u32x4 pack8(const f32x4 a, const f32x4 b) { u32x4 w; w.x = cvt_pk_bf16(a[0], a[1]); w.y = cvt_pk_bf16(a[2], a[3]); w.z = cvt_pk_bf16(b[0], b[1]); w.w = cvt_pk_bf16(b[2], b[3]); return w; }
; __device__ __forceinline__ f32x4 rope2(const f32x4 x, float c0, float s0, float c1, float s1) { return (f32x4){x[0] * c0 - x[1] * s0, x[1] * c0 + x[0] * s0, x[2] * c1 - x[3] * s1, x[3] * c1 + x[2] * s1}; }
;     __device__ __forceinline__ void operator()(const f32x4 (&acc)[2][2][4][2], const pg8::Unit& u, int wr, int wc, int fr, int fq) const {
;     ...
;                 const int row = row0 + ai * 128 + m * 16;
;                 const float rs = 1.0f / sqrtf(SS[(size_t)row * 2] * (1.0f / 512.0f) + 1e-6f);
; #pragma unroll
;                 for (int bj = 0; bj < 2; ++bj) {
;                     const int col8 = u.pn * 256 + bj * 128 + cw, d = col8 % 192;
;                     f32x4 v0 = acc[ai][bj][m][0] * rs, v1 = acc[ai][bj][m][1] * rs;
;                     if (d >= 128) {
;                         const int p0 = (d - 128) >> 1;
;                         const f32x4 c4 = *(const f32x4*)(cosR + (size_t)row * 32 + p0), s4 = *(const f32x4*)(sinR + (size_t)row * 32 + p0);
;                         v0 = rope2(v0, c4[0], s4[0], c4[1], s4[1]); v1 = rope2(v1, c4[2], s4[2], c4[3], s4[3]);
;                     }
;                     *(u32x4*)(QM + (size_t)row * 3072 + col8) = pack8(v0, v1);
.LBB0_1014:
	s_or_b64 exec, exec, s[12:13]
	v_cvt_pk_bf16_f32 v68, v68, v69
	v_cvt_pk_bf16_f32 v69, v70, v71
	v_cvt_pk_bf16_f32 v70, v64, v65
	v_add_u32_e32 v64, 0x80, v148
	v_cvt_pk_bf16_f32 v71, v66, v67
	global_store_dwordx4 v[74:75], v[68:71], off offset:256
	v_ashrrev_i32_e32 v65, 31, v64
	v_lshl_add_u64 v[66:67], v[64:65], 3, s[16:17]
	v_mov_b32_e32 v66, v249
	v_fmamk_f32 v66, v66, 0x3b000000, v176
	v_mul_f32_e32 v67, 0x4f800000, v66
	v_cmp_gt_f32_e32 vcc, s84, v66
	s_nop 1
	v_cndmask_b32_e32 v68, v66, v67, vcc
	v_sqrt_f32_e32 v69, v68
	v_lshlrev_b64 v[66:67], 5, v[64:65]
	v_lshlrev_b64 v[72:73], 2, v[66:67]
	v_add_u32_e32 v65, -1, v69
	v_add_u32_e32 v66, 1, v69
	v_fma_f32 v67, -v65, v69, v68
	v_fma_f32 v70, -v66, v69, v68
	v_cmp_ge_f32_e64 s[12:13], 0, v67
	s_nop 1
	v_cndmask_b32_e64 v65, v69, v65, s[12:13]
	v_cmp_lt_f32_e64 s[12:13], 0, v70
	s_nop 1
	v_cndmask_b32_e64 v65, v65, v66, s[12:13]
	v_mul_f32_e32 v66, 0x37800000, v65
	v_cndmask_b32_e32 v65, v65, v66, vcc
	v_cmp_class_f32_e32 vcc, v68, v177
	v_lshl_add_u64 v[66:67], s[42:43], 0, v[72:73]
	s_nop 0
	v_cndmask_b32_e32 v65, v65, v68, vcc
	v_div_scale_f32 v68, s[12:13], v65, v65, 1.0
	v_rcp_f32_e32 v69, v68
	v_div_scale_f32 v70, vcc, 1.0, v65, 1.0
	v_fma_f32 v71, -v68, v69, 1.0
	v_fmac_f32_e32 v69, v71, v69
	v_mul_f32_e32 v71, v70, v69
	v_fma_f32 v74, -v68, v71, v70
	v_fmac_f32_e32 v71, v74, v69
	v_fma_f32 v68, -v68, v71, v70
	v_div_fmas_f32 v68, v68, v69, v71
	v_div_fixup_f32 v68, v68, v65, 1.0
	v_pk_mul_f32 v[62:63], v[62:63], v[68:69] op_sel_hi:[1,0]
	v_pk_mul_f32 v[60:61], v[60:61], v[68:69] op_sel_hi:[1,0]
	v_pk_mul_f32 v[70:71], v[58:59], v[68:69] op_sel_hi:[1,0]
	v_pk_mul_f32 v[58:59], v[56:57], v[68:69] op_sel_hi:[1,0]
	v_lshl_add_u64 v[56:57], s[44:45], 0, v[72:73]
	s_and_saveexec_b64 s[12:13], s[8:9]
	s_cbranch_execz .LBB0_1016
	v_lshlrev_b64 v[72:73], 2, v[136:137]
	v_lshl_add_u64 v[74:75], v[66:67], 0, v[72:73]
	v_lshl_add_u64 v[76:77], v[56:57], 0, v[72:73]
	global_load_dwordx4 v[72:75], v[74:75], off
	s_nop 0
	global_load_dwordx4 v[76:79], v[76:77], off
	s_waitcnt vmcnt(0)
	v_pk_mul_f32 v[80:81], v[60:61], v[72:73]
	v_pk_mul_f32 v[82:83], v[60:61], v[76:77] op_sel:[1,0] op_sel_hi:[0,0]
	v_pk_mul_f32 v[90:91], v[58:59], v[78:79] op_sel:[1,0] op_sel_hi:[0,0]
	v_mov_b32_e32 v76, v73
	v_mul_f32_e32 v84, v63, v77
	v_mul_f32_e32 v86, v63, v73
	v_pk_mul_f32 v[88:89], v[58:59], v[74:75]
	v_mov_b32_e32 v78, v75
	v_mul_f32_e32 v92, v71, v79
	v_mul_f32_e32 v94, v71, v75
	v_pk_fma_f32 v[60:61], v[60:61], v[72:73], v[82:83] op_sel_hi:[1,0,1]
	v_mov_b32_e32 v72, v77
	v_pk_fma_f32 v[58:59], v[58:59], v[74:75], v[90:91] op_sel_hi:[1,0,1]
	v_mov_b32_e32 v74, v79
	v_pk_fma_f32 v[84:85], v[62:63], v[76:77], v[84:85] op_sel_hi:[1,1,0] neg_lo:[0,0,1] neg_hi:[0,0,1]
	v_pk_fma_f32 v[76:77], v[70:71], v[78:79], v[92:93] op_sel_hi:[1,1,0] neg_lo:[0,0,1] neg_hi:[0,0,1]
	v_pk_fma_f32 v[72:73], v[62:63], v[72:73], v[86:87] op_sel_hi:[1,1,0]
	v_pk_fma_f32 v[74:75], v[70:71], v[74:75], v[94:95] op_sel_hi:[1,1,0]
	v_sub_f32_e32 v60, v80, v82
	v_sub_f32_e32 v58, v88, v90
	v_mov_b32_e32 v62, v84
	v_mov_b32_e32 v70, v76
	v_mov_b32_e32 v63, v72
	v_mov_b32_e32 v71, v74

; __device__ __forceinline__ u32x4 pack8(const f32x4 a, const f32x4 b) { u32x4 w; w.x = cvt_pk_bf16(a[0], a[1]); w.y = cvt_pk_bf16(a[2], a[3]); w.z = cvt_pk_bf16(b[0], b[1]); w.w = cvt_pk_bf16(b[2], b[3]); return w; }
; __device__ __forceinline__ f32x4 rope2(const f32x4 x, float c0, float s0, float c1, float s1) { return (f32x4){x[0] * c0 - x[1] * s0, x[1] * c0 + x[0] * s0, x[2] * c1 - x[3] * s1, x[3] * c1 + x[2] * s1}; }
;     __device__ __forceinline__ void operator()(const f32x4 (&acc)[2][2][4][2], const pg8::Unit& u, int wr, int wc, int fr, int fq) const {
;     ...
;                 const int row = row0 + ai * 128 + m * 16;
;                 const float rs = 1.0f / sqrtf(SS[(size_t)row * 2] * (1.0f / 512.0f) + 1e-6f);
; #pragma unroll
;                 for (int bj = 0; bj < 2; ++bj) {
;                     const int col8 = u.pn * 256 + bj * 128 + cw, d = col8 % 192;
;                     f32x4 v0 = acc[ai][bj][m][0] * rs, v1 = acc[ai][bj][m][1] * rs;
;                     if (d >= 128) {
;                         const int p0 = (d - 128) >> 1;
;                         const f32x4 c4 = *(const f32x4*)(cosR + (size_t)row * 32 + p0), s4 = *(const f32x4*)(sinR + (size_t)row * 32 + p0);
;                         v0 = rope2(v0, c4[0], s4[0], c4[1], s4[1]); v1 = rope2(v1, c4[2], s4[2], c4[3], s4[3]);
;                     }
;                     *(u32x4*)(QM + (size_t)row * 3072 + col8) = pack8(v0, v1);
.LBB0_1018:
	s_or_b64 exec, exec, s[12:13]
	v_cvt_pk_bf16_f32 v52, v52, v53
	v_cvt_pk_bf16_f32 v53, v54, v55
	v_cvt_pk_bf16_f32 v54, v48, v49
	v_add_u32_e32 v48, 0x90, v148
	v_cvt_pk_bf16_f32 v55, v50, v51
	global_store_dwordx4 v[58:59], v[52:55], off offset:256
	v_ashrrev_i32_e32 v49, 31, v48
	v_lshl_add_u64 v[50:51], v[48:49], 3, s[16:17]
	v_mov_b32_e32 v50, v250
	v_fmamk_f32 v50, v50, 0x3b000000, v176
	v_mul_f32_e32 v51, 0x4f800000, v50
	v_cmp_gt_f32_e32 vcc, s84, v50
	s_nop 1
	v_cndmask_b32_e32 v52, v50, v51, vcc
	v_sqrt_f32_e32 v53, v52
	v_lshlrev_b64 v[50:51], 5, v[48:49]
	v_lshlrev_b64 v[56:57], 2, v[50:51]
	v_add_u32_e32 v49, -1, v53
	v_add_u32_e32 v50, 1, v53
	v_fma_f32 v51, -v49, v53, v52
	v_fma_f32 v54, -v50, v53, v52
	v_cmp_ge_f32_e64 s[12:13], 0, v51
	s_nop 1
	v_cndmask_b32_e64 v49, v53, v49, s[12:13]
	v_cmp_lt_f32_e64 s[12:13], 0, v54
	s_nop 1
	v_cndmask_b32_e64 v49, v49, v50, s[12:13]
	v_mul_f32_e32 v50, 0x37800000, v49
	v_cndmask_b32_e32 v49, v49, v50, vcc
	v_cmp_class_f32_e32 vcc, v52, v177
	v_lshl_add_u64 v[50:51], s[42:43], 0, v[56:57]
	s_nop 0
	v_cndmask_b32_e32 v49, v49, v52, vcc
	v_div_scale_f32 v52, s[12:13], v49, v49, 1.0
	v_rcp_f32_e32 v53, v52
	v_div_scale_f32 v54, vcc, 1.0, v49, 1.0
	v_fma_f32 v55, -v52, v53, 1.0
	v_fmac_f32_e32 v53, v55, v53
	v_mul_f32_e32 v55, v54, v53
	v_fma_f32 v58, -v52, v55, v54
	v_fmac_f32_e32 v55, v58, v53
	v_fma_f32 v52, -v52, v55, v54
	v_div_fmas_f32 v52, v52, v53, v55
	v_div_fixup_f32 v52, v52, v49, 1.0
	v_pk_mul_f32 v[46:47], v[46:47], v[52:53] op_sel_hi:[1,0]
	v_pk_mul_f32 v[44:45], v[44:45], v[52:53] op_sel_hi:[1,0]
	v_pk_mul_f32 v[54:55], v[42:43], v[52:53] op_sel_hi:[1,0]
	v_pk_mul_f32 v[42:43], v[40:41], v[52:53] op_sel_hi:[1,0]
	v_lshl_add_u64 v[40:41], s[44:45], 0, v[56:57]
	s_and_saveexec_b64 s[12:13], s[8:9]
	s_cbranch_execz .LBB0_1020
	v_lshlrev_b64 v[56:57], 2, v[136:137]
	v_lshl_add_u64 v[58:59], v[50:51], 0, v[56:57]
	v_lshl_add_u64 v[60:61], v[40:41], 0, v[56:57]
	global_load_dwordx4 v[56:59], v[58:59], off
	s_nop 0
	global_load_dwordx4 v[60:63], v[60:61], off
	s_waitcnt vmcnt(0)
	v_pk_mul_f32 v[64:65], v[44:45], v[56:57]
	v_pk_mul_f32 v[66:67], v[44:45], v[60:61] op_sel:[1,0] op_sel_hi:[0,0]
	v_pk_mul_f32 v[74:75], v[42:43], v[62:63] op_sel:[1,0] op_sel_hi:[0,0]
	v_mov_b32_e32 v60, v57
	v_mul_f32_e32 v68, v47, v61
	v_mul_f32_e32 v70, v47, v57
	v_pk_mul_f32 v[72:73], v[42:43], v[58:59]
	v_mov_b32_e32 v62, v59
	v_mul_f32_e32 v76, v55, v63
	v_mul_f32_e32 v78, v55, v59
	v_pk_fma_f32 v[44:45], v[44:45], v[56:57], v[66:67] op_sel_hi:[1,0,1]
	v_mov_b32_e32 v56, v61
	v_pk_fma_f32 v[42:43], v[42:43], v[58:59], v[74:75] op_sel_hi:[1,0,1]
	v_mov_b32_e32 v58, v63
	v_pk_fma_f32 v[68:69], v[46:47], v[60:61], v[68:69] op_sel_hi:[1,1,0] neg_lo:[0,0,1] neg_hi:[0,0,1]
	v_pk_fma_f32 v[60:61], v[54:55], v[62:63], v[76:77] op_sel_hi:[1,1,0] neg_lo:[0,0,1] neg_hi:[0,0,1]
	v_pk_fma_f32 v[56:57], v[46:47], v[56:57], v[70:71] op_sel_hi:[1,1,0]
	v_pk_fma_f32 v[58:59], v[54:55], v[58:59], v[78:79] op_sel_hi:[1,1,0]
	v_sub_f32_e32 v44, v64, v66
	v_sub_f32_e32 v42, v72, v74
	v_mov_b32_e32 v46, v68
	v_mov_b32_e32 v54, v60
	v_mov_b32_e32 v47, v56
	v_mov_b32_e32 v55, v58

; __device__ __forceinline__ u32x4 pack8(const f32x4 a, const f32x4 b) { u32x4 w; w.x = cvt_pk_bf16(a[0], a[1]); w.y = cvt_pk_bf16(a[2], a[3]); w.z = cvt_pk_bf16(b[0], b[1]); w.w = cvt_pk_bf16(b[2], b[3]); return w; }
; __device__ __forceinline__ f32x4 rope2(const f32x4 x, float c0, float s0, float c1, float s1) { return (f32x4){x[0] * c0 - x[1] * s0, x[1] * c0 + x[0] * s0, x[2] * c1 - x[3] * s1, x[3] * c1 + x[2] * s1}; }
;     __device__ __forceinline__ void operator()(const f32x4 (&acc)[2][2][4][2], const pg8::Unit& u, int wr, int wc, int fr, int fq) const {
;     ...
;                 const int row = row0 + ai * 128 + m * 16;
;                 const float rs = 1.0f / sqrtf(SS[(size_t)row * 2] * (1.0f / 512.0f) + 1e-6f);
; #pragma unroll
;                 for (int bj = 0; bj < 2; ++bj) {
;                     const int col8 = u.pn * 256 + bj * 128 + cw, d = col8 % 192;
;                     f32x4 v0 = acc[ai][bj][m][0] * rs, v1 = acc[ai][bj][m][1] * rs;
;                     if (d >= 128) {
;                         const int p0 = (d - 128) >> 1;
;                         const f32x4 c4 = *(const f32x4*)(cosR + (size_t)row * 32 + p0), s4 = *(const f32x4*)(sinR + (size_t)row * 32 + p0);
;                         v0 = rope2(v0, c4[0], s4[0], c4[1], s4[1]); v1 = rope2(v1, c4[2], s4[2], c4[3], s4[3]);
;                     }
;                     *(u32x4*)(QM + (size_t)row * 3072 + col8) = pack8(v0, v1);
.LBB0_1022:
	s_or_b64 exec, exec, s[12:13]
	v_cvt_pk_bf16_f32 v36, v36, v37
	v_cvt_pk_bf16_f32 v37, v38, v39
	v_cvt_pk_bf16_f32 v38, v32, v33
	v_add_u32_e32 v32, 0xa0, v148
	v_cvt_pk_bf16_f32 v39, v34, v35
	global_store_dwordx4 v[42:43], v[36:39], off offset:256
	v_ashrrev_i32_e32 v33, 31, v32
	v_lshl_add_u64 v[34:35], v[32:33], 3, s[16:17]
	v_mov_b32_e32 v34, v251
	v_fmamk_f32 v34, v34, 0x3b000000, v176
	v_mul_f32_e32 v35, 0x4f800000, v34
	v_cmp_gt_f32_e32 vcc, s84, v34
	s_nop 1
	v_cndmask_b32_e32 v36, v34, v35, vcc
	v_sqrt_f32_e32 v37, v36
	v_lshlrev_b64 v[34:35], 5, v[32:33]
	v_lshlrev_b64 v[40:41], 2, v[34:35]
	v_add_u32_e32 v33, -1, v37
	v_add_u32_e32 v34, 1, v37
	v_fma_f32 v35, -v33, v37, v36
	v_fma_f32 v38, -v34, v37, v36
	v_cmp_ge_f32_e64 s[12:13], 0, v35
	s_nop 1
	v_cndmask_b32_e64 v33, v37, v33, s[12:13]
	v_cmp_lt_f32_e64 s[12:13], 0, v38
	s_nop 1
	v_cndmask_b32_e64 v33, v33, v34, s[12:13]
	v_mul_f32_e32 v34, 0x37800000, v33
	v_cndmask_b32_e32 v33, v33, v34, vcc
	v_cmp_class_f32_e32 vcc, v36, v177
	v_lshl_add_u64 v[34:35], s[42:43], 0, v[40:41]
	s_nop 0
	v_cndmask_b32_e32 v33, v33, v36, vcc
	v_div_scale_f32 v36, s[12:13], v33, v33, 1.0
	v_rcp_f32_e32 v37, v36
	v_div_scale_f32 v38, vcc, 1.0, v33, 1.0
	v_fma_f32 v39, -v36, v37, 1.0
	v_fmac_f32_e32 v37, v39, v37
	v_mul_f32_e32 v39, v38, v37
	v_fma_f32 v42, -v36, v39, v38
	v_fmac_f32_e32 v39, v42, v37
	v_fma_f32 v36, -v36, v39, v38
	v_div_fmas_f32 v36, v36, v37, v39
	v_div_fixup_f32 v36, v36, v33, 1.0
	v_pk_mul_f32 v[30:31], v[30:31], v[36:37] op_sel_hi:[1,0]
	v_pk_mul_f32 v[28:29], v[28:29], v[36:37] op_sel_hi:[1,0]
	v_pk_mul_f32 v[38:39], v[26:27], v[36:37] op_sel_hi:[1,0]
	v_pk_mul_f32 v[26:27], v[24:25], v[36:37] op_sel_hi:[1,0]
	v_lshl_add_u64 v[24:25], s[44:45], 0, v[40:41]
	s_and_saveexec_b64 s[12:13], s[8:9]
	s_cbranch_execz .LBB0_1024
	v_lshlrev_b64 v[40:41], 2, v[136:137]
	v_lshl_add_u64 v[42:43], v[34:35], 0, v[40:41]
	v_lshl_add_u64 v[44:45], v[24:25], 0, v[40:41]
	global_load_dwordx4 v[40:43], v[42:43], off
	s_nop 0
	global_load_dwordx4 v[44:47], v[44:45], off
	s_waitcnt vmcnt(0)
	v_pk_mul_f32 v[48:49], v[28:29], v[40:41]
	v_pk_mul_f32 v[50:51], v[28:29], v[44:45] op_sel:[1,0] op_sel_hi:[0,0]
	v_pk_mul_f32 v[58:59], v[26:27], v[46:47] op_sel:[1,0] op_sel_hi:[0,0]
	v_mov_b32_e32 v44, v41
	v_mul_f32_e32 v52, v31, v45
	v_mul_f32_e32 v54, v31, v41
	v_pk_mul_f32 v[56:57], v[26:27], v[42:43]
	v_mov_b32_e32 v46, v43
	v_mul_f32_e32 v60, v39, v47
	v_mul_f32_e32 v62, v39, v43
	v_pk_fma_f32 v[28:29], v[28:29], v[40:41], v[50:51] op_sel_hi:[1,0,1]
	v_mov_b32_e32 v40, v45
	v_pk_fma_f32 v[26:27], v[26:27], v[42:43], v[58:59] op_sel_hi:[1,0,1]
	v_mov_b32_e32 v42, v47
	v_pk_fma_f32 v[52:53], v[30:31], v[44:45], v[52:53] op_sel_hi:[1,1,0] neg_lo:[0,0,1] neg_hi:[0,0,1]
	v_pk_fma_f32 v[44:45], v[38:39], v[46:47], v[60:61] op_sel_hi:[1,1,0] neg_lo:[0,0,1] neg_hi:[0,0,1]
	v_pk_fma_f32 v[40:41], v[30:31], v[40:41], v[54:55] op_sel_hi:[1,1,0]
	v_pk_fma_f32 v[42:43], v[38:39], v[42:43], v[62:63] op_sel_hi:[1,1,0]
	v_sub_f32_e32 v28, v48, v50
	v_sub_f32_e32 v26, v56, v58
	v_mov_b32_e32 v30, v52
	v_mov_b32_e32 v38, v44
	v_mov_b32_e32 v31, v40
	v_mov_b32_e32 v39, v42

; __device__ __forceinline__ u32x4 pack8(const f32x4 a, const f32x4 b) { u32x4 w; w.x = cvt_pk_bf16(a[0], a[1]); w.y = cvt_pk_bf16(a[2], a[3]); w.z = cvt_pk_bf16(b[0], b[1]); w.w = cvt_pk_bf16(b[2], b[3]); return w; }
; __device__ __forceinline__ f32x4 rope2(const f32x4 x, float c0, float s0, float c1, float s1) { return (f32x4){x[0] * c0 - x[1] * s0, x[1] * c0 + x[0] * s0, x[2] * c1 - x[3] * s1, x[3] * c1 + x[2] * s1}; }
;     __device__ __forceinline__ void operator()(const f32x4 (&acc)[2][2][4][2], const pg8::Unit& u, int wr, int wc, int fr, int fq) const {
;     ...
;                 const int row = row0 + ai * 128 + m * 16;
;                 const float rs = 1.0f / sqrtf(SS[(size_t)row * 2] * (1.0f / 512.0f) + 1e-6f);
; #pragma unroll
;                 for (int bj = 0; bj < 2; ++bj) {
;                     const int col8 = u.pn * 256 + bj * 128 + cw, d = col8 % 192;
;                     f32x4 v0 = acc[ai][bj][m][0] * rs, v1 = acc[ai][bj][m][1] * rs;
;                     if (d >= 128) {
;                         const int p0 = (d - 128) >> 1;
;                         const f32x4 c4 = *(const f32x4*)(cosR + (size_t)row * 32 + p0), s4 = *(const f32x4*)(sinR + (size_t)row * 32 + p0);
;                         v0 = rope2(v0, c4[0], s4[0], c4[1], s4[1]); v1 = rope2(v1, c4[2], s4[2], c4[3], s4[3]);
;                     }
;                     *(u32x4*)(QM + (size_t)row * 3072 + col8) = pack8(v0, v1);
.LBB0_1026:
	s_or_b64 exec, exec, s[12:13]
	v_cvt_pk_bf16_f32 v20, v20, v21
	v_cvt_pk_bf16_f32 v21, v22, v23
	v_cvt_pk_bf16_f32 v22, v16, v17
	v_add_u32_e32 v16, 0xb0, v148
	v_cvt_pk_bf16_f32 v23, v18, v19
	global_store_dwordx4 v[26:27], v[20:23], off offset:256
	v_ashrrev_i32_e32 v17, 31, v16
	v_lshl_add_u64 v[18:19], v[16:17], 3, s[16:17]
	v_mov_b32_e32 v18, v252
	v_fmamk_f32 v18, v18, 0x3b000000, v176
	v_mul_f32_e32 v19, 0x4f800000, v18
	v_cmp_gt_f32_e32 vcc, s84, v18
	s_nop 1
	v_cndmask_b32_e32 v20, v18, v19, vcc
	v_sqrt_f32_e32 v21, v20
	v_lshlrev_b64 v[18:19], 5, v[16:17]
	v_lshlrev_b64 v[24:25], 2, v[18:19]
	v_add_u32_e32 v17, -1, v21
	v_add_u32_e32 v18, 1, v21
	v_fma_f32 v19, -v17, v21, v20
	v_fma_f32 v22, -v18, v21, v20
	v_cmp_ge_f32_e64 s[12:13], 0, v19
	s_nop 1
	v_cndmask_b32_e64 v17, v21, v17, s[12:13]
	v_cmp_lt_f32_e64 s[12:13], 0, v22
	s_nop 1
	v_cndmask_b32_e64 v17, v17, v18, s[12:13]
	v_mul_f32_e32 v18, 0x37800000, v17
	v_cndmask_b32_e32 v17, v17, v18, vcc
	v_cmp_class_f32_e32 vcc, v20, v177
	v_lshl_add_u64 v[18:19], s[42:43], 0, v[24:25]
	s_nop 0
	v_cndmask_b32_e32 v17, v17, v20, vcc
	v_div_scale_f32 v20, s[12:13], v17, v17, 1.0
	v_rcp_f32_e32 v21, v20
	v_div_scale_f32 v22, vcc, 1.0, v17, 1.0
	v_fma_f32 v23, -v20, v21, 1.0
	v_fmac_f32_e32 v21, v23, v21
	v_mul_f32_e32 v23, v22, v21
	v_fma_f32 v26, -v20, v23, v22
	v_fmac_f32_e32 v23, v26, v21
	v_fma_f32 v20, -v20, v23, v22
	v_div_fmas_f32 v20, v20, v21, v23
	v_div_fixup_f32 v20, v20, v17, 1.0
	v_pk_mul_f32 v[14:15], v[14:15], v[20:21] op_sel_hi:[1,0]
	v_pk_mul_f32 v[12:13], v[12:13], v[20:21] op_sel_hi:[1,0]
	v_pk_mul_f32 v[22:23], v[10:11], v[20:21] op_sel_hi:[1,0]
	v_pk_mul_f32 v[10:11], v[8:9], v[20:21] op_sel_hi:[1,0]
	v_lshl_add_u64 v[8:9], s[44:45], 0, v[24:25]
	s_and_saveexec_b64 s[12:13], s[8:9]
	s_cbranch_execz .LBB0_1028
	v_lshlrev_b64 v[24:25], 2, v[136:137]
	v_lshl_add_u64 v[26:27], v[18:19], 0, v[24:25]
	v_lshl_add_u64 v[28:29], v[8:9], 0, v[24:25]
	global_load_dwordx4 v[24:27], v[26:27], off
	s_nop 0
	global_load_dwordx4 v[28:31], v[28:29], off
	s_waitcnt vmcnt(0)
	v_pk_mul_f32 v[32:33], v[12:13], v[24:25]
	v_pk_mul_f32 v[34:35], v[12:13], v[28:29] op_sel:[1,0] op_sel_hi:[0,0]
	v_pk_mul_f32 v[42:43], v[10:11], v[30:31] op_sel:[1,0] op_sel_hi:[0,0]
	v_mov_b32_e32 v28, v25
	v_mul_f32_e32 v36, v15, v29
	v_mul_f32_e32 v38, v15, v25
	v_pk_mul_f32 v[40:41], v[10:11], v[26:27]
	v_mov_b32_e32 v30, v27
	v_mul_f32_e32 v44, v23, v31
	v_mul_f32_e32 v46, v23, v27
	v_pk_fma_f32 v[12:13], v[12:13], v[24:25], v[34:35] op_sel_hi:[1,0,1]
	v_mov_b32_e32 v24, v29
	v_pk_fma_f32 v[10:11], v[10:11], v[26:27], v[42:43] op_sel_hi:[1,0,1]
	v_mov_b32_e32 v26, v31
	v_pk_fma_f32 v[36:37], v[14:15], v[28:29], v[36:37] op_sel_hi:[1,1,0] neg_lo:[0,0,1] neg_hi:[0,0,1]
	v_pk_fma_f32 v[28:29], v[22:23], v[30:31], v[44:45] op_sel_hi:[1,1,0] neg_lo:[0,0,1] neg_hi:[0,0,1]
	v_pk_fma_f32 v[24:25], v[14:15], v[24:25], v[38:39] op_sel_hi:[1,1,0]
	v_pk_fma_f32 v[26:27], v[22:23], v[26:27], v[46:47] op_sel_hi:[1,1,0]
	v_sub_f32_e32 v12, v32, v34
	v_sub_f32_e32 v10, v40, v42
	v_mov_b32_e32 v14, v36
	v_mov_b32_e32 v22, v28
	v_mov_b32_e32 v15, v24
	v_mov_b32_e32 v23, v26
